# P7 residual GEMM epilogue: x loads streamed 7 pairs deep instead of one pair per vmcnt(0); row sums reduced in one batch
# speedup vs baseline: 1.0268x; 1.0103x over previous
.LBB0_643:
	v_and_b32_e32 v156, 64, v215
	v_xor_b32_e32 v147, 16, v215
	v_add_u32_e32 v156, 64, v156
	v_cmp_lt_i32_e32 vcc, v147, v156
	s_cmpk_lt_i32 s10, 0x80
	v_lshl_add_u32 v146, s10, 8, v150
	v_cndmask_b32_e32 v147, v215, v147, vcc
	v_lshlrev_b32_e32 v157, 2, v147
	v_xor_b32_e32 v147, 32, v215
	v_cmp_lt_i32_e32 vcc, v147, v156
	v_lshl_or_b32 v144, s2, 8, v152
	s_cselect_b32 s10, s45, s62
	s_cselect_b32 s11, s44, s61
	v_cndmask_b32_e32 v147, v215, v147, vcc
	v_mov_b32_e32 v148, s11
	v_mov_b32_e32 v149, s10
	v_ashrrev_i32_e32 v145, 31, v144
	v_lshlrev_b32_e32 v156, 2, v147
	v_ashrrev_i32_e32 v147, 31, v146
	v_lshl_add_u64 v[148:149], v[144:145], 2, v[148:149]
	v_lshlrev_b64 v[158:159], 12, v[146:147]
	v_lshl_add_u64 v[148:149], v[148:149], 0, v[158:159]
	s_lshl_b32 s10, s2, 2
	s_ashr_i32 s11, s10, 31
	s_lshl_b32 s2, s23, 2
	v_lshlrev_b64 v[158:159], 6, v[146:147]
	v_lshlrev_b64 v[146:147], 11, v[146:147]
	v_lshl_add_u64 v[158:159], s[0:1], 0, v[158:159]
	v_lshl_add_u64 v[146:147], s[96:97], 0, v[146:147]
	v_lshl_add_u64 v[158:159], s[10:11], 2, v[158:159]
	v_lshl_add_u64 v[144:145], v[144:145], 1, v[146:147]
	v_lshl_add_u64 v[146:147], v[158:159], 0, s[2:3]
	s_mov_b64 s[10:11], 0x10000
	s_mov_b64 s[12:13], 0x8000
	global_load_dwordx4 v[160:163], v[148:149], off
	global_load_dwordx4 v[164:167], v[148:149], off offset:16
	global_load_dwordx4 v[168:171], v[148:149], off offset:512
	global_load_dwordx4 v[172:175], v[148:149], off offset:528
	v_lshl_add_u64 v[148:149], v[148:149], 0, s[10:11]
	global_load_dwordx4 v[176:179], v[148:149], off
	global_load_dwordx4 v[180:183], v[148:149], off offset:16
	global_load_dwordx4 v[184:187], v[148:149], off offset:512
	global_load_dwordx4 v[188:191], v[148:149], off offset:528
	v_lshl_add_u64 v[148:149], v[148:149], 0, s[10:11]
	global_load_dwordx4 v[192:195], v[148:149], off
	global_load_dwordx4 v[196:199], v[148:149], off offset:16
	global_load_dwordx4 v[200:203], v[148:149], off offset:512
	global_load_dwordx4 v[204:207], v[148:149], off offset:528
	v_lshl_add_u64 v[148:149], v[148:149], 0, s[10:11]
	global_load_dwordx4 v[208:211], v[148:149], off
	global_load_dwordx4 v[216:219], v[148:149], off offset:16
	s_waitcnt vmcnt(12)
	v_pk_add_f32 v[124:125], v[124:125], v[160:161]
	v_pk_add_f32 v[126:127], v[126:127], v[162:163]
	v_pk_add_f32 v[120:121], v[120:121], v[164:165]
	v_pk_add_f32 v[122:123], v[122:123], v[166:167]
	global_load_dwordx4 v[160:163], v[148:149], off offset:512
	global_load_dwordx4 v[164:167], v[148:149], off offset:528
	s_mov_b64 s[10:11], 0x50000
	v_lshl_add_u64 v[148:149], v[148:149], 0, s[10:11]
	s_mov_b64 s[10:11], 0x10000
	v_mul_f32_e32 v158, v125, v125
	v_mul_f32_e32 v159, v127, v127
	v_fmac_f32_e32 v158, v124, v124
	v_fmac_f32_e32 v159, v126, v126
	v_add_f32_e32 v158, v158, v159
	v_mul_f32_e32 v159, v121, v121
	v_fmac_f32_e32 v159, v120, v120
	v_add_f32_e32 v158, v158, v159
	v_mul_f32_e32 v159, v123, v123
	v_fmac_f32_e32 v159, v122, v122
	v_add_f32_e32 v158, v159, v158
	v_cvt_pk_bf16_f32 v124, v124, v125
	v_cvt_pk_bf16_f32 v125, v126, v127
	v_cvt_pk_bf16_f32 v126, v120, v121
	v_cvt_pk_bf16_f32 v127, v122, v123
	global_store_dwordx4 v[144:145], v[124:127], off
	v_mov_b32_e32 v120, v158
	s_waitcnt vmcnt(13)
	v_pk_add_f32 v[116:117], v[116:117], v[168:169]
	v_pk_add_f32 v[118:119], v[118:119], v[170:171]
	v_pk_add_f32 v[112:113], v[112:113], v[172:173]
	v_pk_add_f32 v[114:115], v[114:115], v[174:175]
	global_load_dwordx4 v[168:171], v[148:149], off
	global_load_dwordx4 v[172:175], v[148:149], off offset:16
	v_mul_f32_e32 v158, v117, v117
	v_mul_f32_e32 v159, v119, v119
	v_fmac_f32_e32 v158, v116, v116
	v_fmac_f32_e32 v159, v118, v118
	v_add_f32_e32 v158, v158, v159
	v_mul_f32_e32 v159, v113, v113
	v_fmac_f32_e32 v159, v112, v112
	v_add_f32_e32 v158, v158, v159
	v_mul_f32_e32 v159, v115, v115
	v_fmac_f32_e32 v159, v114, v114
	v_add_f32_e32 v158, v159, v158
	v_cvt_pk_bf16_f32 v116, v116, v117
	v_cvt_pk_bf16_f32 v117, v118, v119
	v_cvt_pk_bf16_f32 v118, v112, v113
	v_cvt_pk_bf16_f32 v119, v114, v115
	global_store_dwordx4 v[144:145], v[116:119], off offset:256
	v_add_f32_e32 v112, v120, v158
	v_lshl_add_u64 v[144:145], v[144:145], 0, s[12:13]
	s_waitcnt vmcnt(14)
	v_pk_add_f32 v[108:109], v[108:109], v[176:177]
	v_pk_add_f32 v[110:111], v[110:111], v[178:179]
	v_pk_add_f32 v[104:105], v[104:105], v[180:181]
	v_pk_add_f32 v[106:107], v[106:107], v[182:183]
	global_load_dwordx4 v[176:179], v[148:149], off offset:512
	global_load_dwordx4 v[180:183], v[148:149], off offset:528
	v_lshl_add_u64 v[148:149], v[148:149], 0, s[10:11]
	v_mul_f32_e32 v158, v109, v109
	v_mul_f32_e32 v159, v111, v111
	v_fmac_f32_e32 v158, v108, v108
	v_fmac_f32_e32 v159, v110, v110
	v_add_f32_e32 v158, v158, v159
	v_mul_f32_e32 v159, v105, v105
	v_fmac_f32_e32 v159, v104, v104
	v_add_f32_e32 v158, v158, v159
	v_mul_f32_e32 v159, v107, v107
	v_fmac_f32_e32 v159, v106, v106
	v_add_f32_e32 v158, v159, v158
	v_cvt_pk_bf16_f32 v108, v108, v109
	v_cvt_pk_bf16_f32 v109, v110, v111
	v_cvt_pk_bf16_f32 v110, v104, v105
	v_cvt_pk_bf16_f32 v111, v106, v107
	global_store_dwordx4 v[144:145], v[108:111], off
	v_mov_b32_e32 v104, v158
	s_waitcnt vmcnt(15)
	v_pk_add_f32 v[100:101], v[100:101], v[184:185]
	v_pk_add_f32 v[102:103], v[102:103], v[186:187]
	v_pk_add_f32 v[96:97], v[96:97], v[188:189]
	v_pk_add_f32 v[98:99], v[98:99], v[190:191]
	global_load_dwordx4 v[184:187], v[148:149], off
	global_load_dwordx4 v[188:191], v[148:149], off offset:16
	v_mul_f32_e32 v158, v101, v101
	v_mul_f32_e32 v159, v103, v103
	v_fmac_f32_e32 v158, v100, v100
	v_fmac_f32_e32 v159, v102, v102
	v_add_f32_e32 v158, v158, v159
	v_mul_f32_e32 v159, v97, v97
	v_fmac_f32_e32 v159, v96, v96
	v_add_f32_e32 v158, v158, v159
	v_mul_f32_e32 v159, v99, v99
	v_fmac_f32_e32 v159, v98, v98
	v_add_f32_e32 v158, v159, v158
	v_cvt_pk_bf16_f32 v100, v100, v101
	v_cvt_pk_bf16_f32 v101, v102, v103
	v_cvt_pk_bf16_f32 v102, v96, v97
	v_cvt_pk_bf16_f32 v103, v98, v99
	global_store_dwordx4 v[144:145], v[100:103], off offset:256
	v_add_f32_e32 v96, v104, v158
	v_lshl_add_u64 v[144:145], v[144:145], 0, s[12:13]
	s_waitcnt vmcnt(16)
	v_pk_add_f32 v[92:93], v[92:93], v[192:193]
	v_pk_add_f32 v[94:95], v[94:95], v[194:195]
	v_pk_add_f32 v[88:89], v[88:89], v[196:197]
	v_pk_add_f32 v[90:91], v[90:91], v[198:199]
	global_load_dwordx4 v[192:195], v[148:149], off offset:512
	global_load_dwordx4 v[196:199], v[148:149], off offset:528
	v_lshl_add_u64 v[148:149], v[148:149], 0, s[10:11]
	v_mul_f32_e32 v158, v93, v93
	v_mul_f32_e32 v159, v95, v95
	v_fmac_f32_e32 v158, v92, v92
	v_fmac_f32_e32 v159, v94, v94
	v_add_f32_e32 v158, v158, v159
	v_mul_f32_e32 v159, v89, v89
	v_fmac_f32_e32 v159, v88, v88
	v_add_f32_e32 v158, v158, v159
	v_mul_f32_e32 v159, v91, v91
	v_fmac_f32_e32 v159, v90, v90
	v_add_f32_e32 v158, v159, v158
	v_cvt_pk_bf16_f32 v92, v92, v93
	v_cvt_pk_bf16_f32 v93, v94, v95
	v_cvt_pk_bf16_f32 v94, v88, v89
	v_cvt_pk_bf16_f32 v95, v90, v91
	global_store_dwordx4 v[144:145], v[92:95], off
	v_mov_b32_e32 v88, v158
	s_waitcnt vmcnt(17)
	v_pk_add_f32 v[84:85], v[84:85], v[200:201]
	v_pk_add_f32 v[86:87], v[86:87], v[202:203]
	v_pk_add_f32 v[80:81], v[80:81], v[204:205]
	v_pk_add_f32 v[82:83], v[82:83], v[206:207]
	global_load_dwordx4 v[200:203], v[148:149], off
	global_load_dwordx4 v[204:207], v[148:149], off offset:16
	v_mul_f32_e32 v158, v85, v85
	v_mul_f32_e32 v159, v87, v87
	v_fmac_f32_e32 v158, v84, v84
	v_fmac_f32_e32 v159, v86, v86
	v_add_f32_e32 v158, v158, v159
	v_mul_f32_e32 v159, v81, v81
	v_fmac_f32_e32 v159, v80, v80
	v_add_f32_e32 v158, v158, v159
	v_mul_f32_e32 v159, v83, v83
	v_fmac_f32_e32 v159, v82, v82
	v_add_f32_e32 v158, v159, v158
	v_cvt_pk_bf16_f32 v84, v84, v85
	v_cvt_pk_bf16_f32 v85, v86, v87
	v_cvt_pk_bf16_f32 v86, v80, v81
	v_cvt_pk_bf16_f32 v87, v82, v83
	global_store_dwordx4 v[144:145], v[84:87], off offset:256
	v_add_f32_e32 v80, v88, v158
	v_lshl_add_u64 v[144:145], v[144:145], 0, s[12:13]
	s_waitcnt vmcnt(18)
	v_pk_add_f32 v[76:77], v[76:77], v[208:209]
	v_pk_add_f32 v[78:79], v[78:79], v[210:211]
	v_pk_add_f32 v[72:73], v[72:73], v[216:217]
	v_pk_add_f32 v[74:75], v[74:75], v[218:219]
	global_load_dwordx4 v[208:211], v[148:149], off offset:512
	global_load_dwordx4 v[216:219], v[148:149], off offset:528
	v_lshl_add_u64 v[148:149], v[148:149], 0, s[10:11]
	v_mul_f32_e32 v158, v77, v77
	v_mul_f32_e32 v159, v79, v79
	v_fmac_f32_e32 v158, v76, v76
	v_fmac_f32_e32 v159, v78, v78
	v_add_f32_e32 v158, v158, v159
	v_mul_f32_e32 v159, v73, v73
	v_fmac_f32_e32 v159, v72, v72
	v_add_f32_e32 v158, v158, v159
	v_mul_f32_e32 v159, v75, v75
	v_fmac_f32_e32 v159, v74, v74
	v_add_f32_e32 v158, v159, v158
	v_cvt_pk_bf16_f32 v76, v76, v77
	v_cvt_pk_bf16_f32 v77, v78, v79
	v_cvt_pk_bf16_f32 v78, v72, v73
	v_cvt_pk_bf16_f32 v79, v74, v75
	global_store_dwordx4 v[144:145], v[76:79], off
	v_mov_b32_e32 v72, v158
	s_waitcnt vmcnt(19)
	v_pk_add_f32 v[68:69], v[68:69], v[160:161]
	v_pk_add_f32 v[70:71], v[70:71], v[162:163]
	v_pk_add_f32 v[64:65], v[64:65], v[164:165]
	v_pk_add_f32 v[66:67], v[66:67], v[166:167]
	global_load_dwordx4 v[160:163], v[148:149], off
	global_load_dwordx4 v[164:167], v[148:149], off offset:16
	v_mul_f32_e32 v158, v69, v69
	v_mul_f32_e32 v159, v71, v71
	v_fmac_f32_e32 v158, v68, v68
	v_fmac_f32_e32 v159, v70, v70
	v_add_f32_e32 v158, v158, v159
	v_mul_f32_e32 v159, v65, v65
	v_fmac_f32_e32 v159, v64, v64
	v_add_f32_e32 v158, v158, v159
	v_mul_f32_e32 v159, v67, v67
	v_fmac_f32_e32 v159, v66, v66
	v_add_f32_e32 v158, v159, v158
	v_cvt_pk_bf16_f32 v68, v68, v69
	v_cvt_pk_bf16_f32 v69, v70, v71
	v_cvt_pk_bf16_f32 v70, v64, v65
	v_cvt_pk_bf16_f32 v71, v66, v67
	global_store_dwordx4 v[144:145], v[68:71], off offset:256
	v_add_f32_e32 v64, v72, v158
	s_mov_b64 s[12:13], 0x28000
	v_lshl_add_u64 v[144:145], v[144:145], 0, s[12:13]
	s_mov_b64 s[12:13], 0x8000
	s_waitcnt vmcnt(19)
	v_pk_add_f32 v[60:61], v[60:61], v[168:169]
	v_pk_add_f32 v[62:63], v[62:63], v[170:171]
	v_pk_add_f32 v[56:57], v[56:57], v[172:173]
	v_pk_add_f32 v[58:59], v[58:59], v[174:175]
	global_load_dwordx4 v[168:171], v[148:149], off offset:512
	global_load_dwordx4 v[172:175], v[148:149], off offset:528
	v_mul_f32_e32 v158, v61, v61
	v_mul_f32_e32 v159, v63, v63
	v_fmac_f32_e32 v158, v60, v60
	v_fmac_f32_e32 v159, v62, v62
	v_add_f32_e32 v158, v158, v159
	v_mul_f32_e32 v159, v57, v57
	v_fmac_f32_e32 v159, v56, v56
	v_add_f32_e32 v158, v158, v159
	v_mul_f32_e32 v159, v59, v59
	v_fmac_f32_e32 v159, v58, v58
	v_add_f32_e32 v158, v159, v158
	v_cvt_pk_bf16_f32 v60, v60, v61
	v_cvt_pk_bf16_f32 v61, v62, v63
	v_cvt_pk_bf16_f32 v62, v56, v57
	v_cvt_pk_bf16_f32 v63, v58, v59
	global_store_dwordx4 v[144:145], v[60:63], off
	v_mov_b32_e32 v56, v158
	s_waitcnt vmcnt(19)
	v_pk_add_f32 v[52:53], v[52:53], v[176:177]
	v_pk_add_f32 v[54:55], v[54:55], v[178:179]
	v_pk_add_f32 v[48:49], v[48:49], v[180:181]
	v_pk_add_f32 v[50:51], v[50:51], v[182:183]
	v_mul_f32_e32 v158, v53, v53
	v_mul_f32_e32 v159, v55, v55
	v_fmac_f32_e32 v158, v52, v52
	v_fmac_f32_e32 v159, v54, v54
	v_add_f32_e32 v158, v158, v159
	v_mul_f32_e32 v159, v49, v49
	v_fmac_f32_e32 v159, v48, v48
	v_add_f32_e32 v158, v158, v159
	v_mul_f32_e32 v159, v51, v51
	v_fmac_f32_e32 v159, v50, v50
	v_add_f32_e32 v158, v159, v158
	v_cvt_pk_bf16_f32 v52, v52, v53
	v_cvt_pk_bf16_f32 v53, v54, v55
	v_cvt_pk_bf16_f32 v54, v48, v49
	v_cvt_pk_bf16_f32 v55, v50, v51
	global_store_dwordx4 v[144:145], v[52:55], off offset:256
	v_add_f32_e32 v48, v56, v158
	v_lshl_add_u64 v[144:145], v[144:145], 0, s[12:13]
	s_waitcnt vmcnt(17)
	v_pk_add_f32 v[44:45], v[44:45], v[184:185]
	v_pk_add_f32 v[46:47], v[46:47], v[186:187]
	v_pk_add_f32 v[40:41], v[40:41], v[188:189]
	v_pk_add_f32 v[42:43], v[42:43], v[190:191]
	v_mul_f32_e32 v158, v45, v45
	v_mul_f32_e32 v159, v47, v47
	v_fmac_f32_e32 v158, v44, v44
	v_fmac_f32_e32 v159, v46, v46
	v_add_f32_e32 v158, v158, v159
	v_mul_f32_e32 v159, v41, v41
	v_fmac_f32_e32 v159, v40, v40
	v_add_f32_e32 v158, v158, v159
	v_mul_f32_e32 v159, v43, v43
	v_fmac_f32_e32 v159, v42, v42
	v_add_f32_e32 v158, v159, v158
	v_cvt_pk_bf16_f32 v44, v44, v45
	v_cvt_pk_bf16_f32 v45, v46, v47
	v_cvt_pk_bf16_f32 v46, v40, v41
	v_cvt_pk_bf16_f32 v47, v42, v43
	global_store_dwordx4 v[144:145], v[44:47], off
	v_mov_b32_e32 v40, v158
	s_waitcnt vmcnt(15)
	v_pk_add_f32 v[36:37], v[36:37], v[192:193]
	v_pk_add_f32 v[38:39], v[38:39], v[194:195]
	v_pk_add_f32 v[32:33], v[32:33], v[196:197]
	v_pk_add_f32 v[34:35], v[34:35], v[198:199]
	v_mul_f32_e32 v158, v37, v37
	v_mul_f32_e32 v159, v39, v39
	v_fmac_f32_e32 v158, v36, v36
	v_fmac_f32_e32 v159, v38, v38
	v_add_f32_e32 v158, v158, v159
	v_mul_f32_e32 v159, v33, v33
	v_fmac_f32_e32 v159, v32, v32
	v_add_f32_e32 v158, v158, v159
	v_mul_f32_e32 v159, v35, v35
	v_fmac_f32_e32 v159, v34, v34
	v_add_f32_e32 v158, v159, v158
	v_cvt_pk_bf16_f32 v36, v36, v37
	v_cvt_pk_bf16_f32 v37, v38, v39
	v_cvt_pk_bf16_f32 v38, v32, v33
	v_cvt_pk_bf16_f32 v39, v34, v35
	global_store_dwordx4 v[144:145], v[36:39], off offset:256
	v_add_f32_e32 v32, v40, v158
	v_lshl_add_u64 v[144:145], v[144:145], 0, s[12:13]
	s_waitcnt vmcnt(13)
	v_pk_add_f32 v[28:29], v[28:29], v[200:201]
	v_pk_add_f32 v[30:31], v[30:31], v[202:203]
	v_pk_add_f32 v[24:25], v[24:25], v[204:205]
	v_pk_add_f32 v[26:27], v[26:27], v[206:207]
	v_mul_f32_e32 v158, v29, v29
	v_mul_f32_e32 v159, v31, v31
	v_fmac_f32_e32 v158, v28, v28
	v_fmac_f32_e32 v159, v30, v30
	v_add_f32_e32 v158, v158, v159
	v_mul_f32_e32 v159, v25, v25
	v_fmac_f32_e32 v159, v24, v24
	v_add_f32_e32 v158, v158, v159
	v_mul_f32_e32 v159, v27, v27
	v_fmac_f32_e32 v159, v26, v26
	v_add_f32_e32 v158, v159, v158
	v_cvt_pk_bf16_f32 v28, v28, v29
	v_cvt_pk_bf16_f32 v29, v30, v31
	v_cvt_pk_bf16_f32 v30, v24, v25
	v_cvt_pk_bf16_f32 v31, v26, v27
	global_store_dwordx4 v[144:145], v[28:31], off
	v_mov_b32_e32 v24, v158
	s_waitcnt vmcnt(11)
	v_pk_add_f32 v[20:21], v[20:21], v[208:209]
	v_pk_add_f32 v[22:23], v[22:23], v[210:211]
	v_pk_add_f32 v[16:17], v[16:17], v[216:217]
	v_pk_add_f32 v[18:19], v[18:19], v[218:219]
	v_mul_f32_e32 v158, v21, v21
	v_mul_f32_e32 v159, v23, v23
	v_fmac_f32_e32 v158, v20, v20
	v_fmac_f32_e32 v159, v22, v22
	v_add_f32_e32 v158, v158, v159
	v_mul_f32_e32 v159, v17, v17
	v_fmac_f32_e32 v159, v16, v16
	v_add_f32_e32 v158, v158, v159
	v_mul_f32_e32 v159, v19, v19
	v_fmac_f32_e32 v159, v18, v18
	v_add_f32_e32 v158, v159, v158
	v_cvt_pk_bf16_f32 v20, v20, v21
	v_cvt_pk_bf16_f32 v21, v22, v23
	v_cvt_pk_bf16_f32 v22, v16, v17
	v_cvt_pk_bf16_f32 v23, v18, v19
	global_store_dwordx4 v[144:145], v[20:23], off offset:256
	v_add_f32_e32 v16, v24, v158
	v_lshl_add_u64 v[144:145], v[144:145], 0, s[12:13]
	s_waitcnt vmcnt(9)
	v_pk_add_f32 v[12:13], v[12:13], v[160:161]
	v_pk_add_f32 v[14:15], v[14:15], v[162:163]
	v_pk_add_f32 v[8:9], v[8:9], v[164:165]
	v_pk_add_f32 v[10:11], v[10:11], v[166:167]
	v_mul_f32_e32 v158, v13, v13
	v_mul_f32_e32 v159, v15, v15
	v_fmac_f32_e32 v158, v12, v12
	v_fmac_f32_e32 v159, v14, v14
	v_add_f32_e32 v158, v158, v159
	v_mul_f32_e32 v159, v9, v9
	v_fmac_f32_e32 v159, v8, v8
	v_add_f32_e32 v158, v158, v159
	v_mul_f32_e32 v159, v11, v11
	v_fmac_f32_e32 v159, v10, v10
	v_add_f32_e32 v158, v159, v158
	v_cvt_pk_bf16_f32 v12, v12, v13
	v_cvt_pk_bf16_f32 v13, v14, v15
	v_cvt_pk_bf16_f32 v14, v8, v9
	v_cvt_pk_bf16_f32 v15, v10, v11
	global_store_dwordx4 v[144:145], v[12:15], off
	v_mov_b32_e32 v8, v158
	s_waitcnt vmcnt(7)
	v_pk_add_f32 v[4:5], v[4:5], v[168:169]
	v_pk_add_f32 v[6:7], v[6:7], v[170:171]
	v_pk_add_f32 v[0:1], v[0:1], v[172:173]
	v_pk_add_f32 v[2:3], v[2:3], v[174:175]
	v_mul_f32_e32 v158, v5, v5
	v_mul_f32_e32 v159, v7, v7
	v_fmac_f32_e32 v158, v4, v4
	v_fmac_f32_e32 v159, v6, v6
	v_add_f32_e32 v158, v158, v159
	v_mul_f32_e32 v159, v1, v1
	v_fmac_f32_e32 v159, v0, v0
	v_add_f32_e32 v158, v158, v159
	v_mul_f32_e32 v159, v3, v3
	v_fmac_f32_e32 v159, v2, v2
	v_add_f32_e32 v158, v159, v158
	v_cvt_pk_bf16_f32 v4, v4, v5
	v_cvt_pk_bf16_f32 v5, v6, v7
	v_cvt_pk_bf16_f32 v6, v0, v1
	v_cvt_pk_bf16_f32 v7, v2, v3
	global_store_dwordx4 v[144:145], v[4:7], off offset:256
	v_add_f32_e32 v0, v8, v158
	s_mov_b64 s[10:11], 0x2000
	v_lshl_add_u64 v[148:149], v[146:147], 0, s[10:11]
	ds_bpermute_b32 v113, v157, v112
	ds_bpermute_b32 v97, v157, v96
	ds_bpermute_b32 v81, v157, v80
	ds_bpermute_b32 v65, v157, v64
	ds_bpermute_b32 v49, v157, v48
	ds_bpermute_b32 v33, v157, v32
	ds_bpermute_b32 v17, v157, v16
	ds_bpermute_b32 v1, v157, v0
	s_waitcnt lgkmcnt(7)
	v_add_f32_e32 v112, v112, v113
	s_waitcnt lgkmcnt(6)
	v_add_f32_e32 v96, v96, v97
	s_waitcnt lgkmcnt(5)
	v_add_f32_e32 v80, v80, v81
	s_waitcnt lgkmcnt(4)
	v_add_f32_e32 v64, v64, v65
	s_waitcnt lgkmcnt(3)
	v_add_f32_e32 v48, v48, v49
	s_waitcnt lgkmcnt(2)
	v_add_f32_e32 v32, v32, v33
	s_waitcnt lgkmcnt(1)
	v_add_f32_e32 v16, v16, v17
	s_waitcnt lgkmcnt(0)
	v_add_f32_e32 v0, v0, v1
	ds_bpermute_b32 v113, v156, v112
	ds_bpermute_b32 v97, v156, v96
	ds_bpermute_b32 v81, v156, v80
	ds_bpermute_b32 v65, v156, v64
	ds_bpermute_b32 v49, v156, v48
	ds_bpermute_b32 v33, v156, v32
	ds_bpermute_b32 v17, v156, v16
	ds_bpermute_b32 v1, v156, v0
	s_waitcnt lgkmcnt(7)
	v_add_f32_e32 v112, v112, v113
	s_waitcnt lgkmcnt(6)
	v_add_f32_e32 v96, v96, v97
	s_waitcnt lgkmcnt(5)
	v_add_f32_e32 v80, v80, v81
	s_waitcnt lgkmcnt(4)
	v_add_f32_e32 v64, v64, v65
	s_waitcnt lgkmcnt(3)
	v_add_f32_e32 v48, v48, v49
	s_waitcnt lgkmcnt(2)
	v_add_f32_e32 v32, v32, v33
	s_waitcnt lgkmcnt(1)
	v_add_f32_e32 v16, v16, v17
	s_waitcnt lgkmcnt(0)
	v_add_f32_e32 v0, v0, v1
	s_and_saveexec_b64 s[12:13], s[40:41]
	global_store_dword v[146:147], v112, off
	global_store_dword v[146:147], v96, off offset:1024
	global_store_dword v[146:147], v80, off offset:2048
	global_store_dword v[146:147], v64, off offset:3072
	global_store_dword v[148:149], v48, off
	global_store_dword v[148:149], v32, off offset:1024
	global_store_dword v[148:149], v16, off offset:2048
	global_store_dword v[148:149], v0, off offset:3072
	s_or_b64 exec, exec, s[12:13]
	s_andn2_b64 vcc, exec, s[42:43]
	s_mov_b64 s[10:11], -1
	s_cbranch_vccnz .LBB0_632
	s_andn2_b64 vcc, exec, s[4:5]
	s_cbranch_vccnz .LBB0_631
	s_barrier
	s_branch .LBB0_631
